# speedup vs baseline: 1.0063x; 1.0063x over previous
; template <class Epi, class Sched, bool ALIGN_EPI = false, bool SP2 = false>
; __device__ __forceinline__ void gemm_phase(PG8_LAS unsigned char* lds, const Gemm g, const Sched& S, const Epi& E) {
;     ...
; #pragma unroll
;         for (int a = 0; a < 2; ++a)
; #pragma unroll
;             for (int b = 0; b < 2; ++b)
; #pragma unroll
;                 for (int m = 0; m < 4; ++m)
; #pragma unroll
;                     for (int n = 0; n < 2; ++n) acc[a][b][m][n] = (f32x4){0.f, 0.f, 0.f, 0.f};
.LBB0_298:
	s_add_u32 s68, s42, 0x100
	v_mov_b32_e32 v4, 0
	s_addc_u32 s69, s43, 0
	s_mov_b32 s70, -2
	v_mov_b32_e32 v5, v4
	v_mov_b64_e32 v[6:7], v[4:5]
	v_mov_b64_e32 v[8:9], v[4:5]
	v_mov_b64_e32 v[10:11], v[4:5]
	v_mov_b64_e32 v[12:13], v[4:5]
	v_mov_b64_e32 v[14:15], v[4:5]
	v_mov_b64_e32 v[16:17], v[4:5]
	v_mov_b64_e32 v[18:19], v[4:5]
	v_mov_b64_e32 v[20:21], v[4:5]
	v_mov_b64_e32 v[22:23], v[4:5]
	v_mov_b64_e32 v[24:25], v[4:5]
	v_mov_b64_e32 v[26:27], v[4:5]
	v_mov_b64_e32 v[28:29], v[4:5]
	v_mov_b64_e32 v[30:31], v[4:5]
	v_mov_b64_e32 v[32:33], v[4:5]
	v_mov_b64_e32 v[34:35], v[4:5]
	v_mov_b64_e32 v[36:37], v[4:5]
	v_mov_b64_e32 v[38:39], v[4:5]
	v_mov_b64_e32 v[40:41], v[4:5]
	v_mov_b64_e32 v[42:43], v[4:5]
	v_mov_b64_e32 v[44:45], v[4:5]
	v_mov_b64_e32 v[46:47], v[4:5]
	v_mov_b64_e32 v[48:49], v[4:5]
	v_mov_b64_e32 v[50:51], v[4:5]
	v_mov_b64_e32 v[52:53], v[4:5]
	v_mov_b64_e32 v[54:55], v[4:5]
	v_mov_b64_e32 v[56:57], v[4:5]
	v_mov_b64_e32 v[58:59], v[4:5]
	v_mov_b64_e32 v[60:61], v[4:5]
	v_mov_b64_e32 v[62:63], v[4:5]
	v_mov_b64_e32 v[64:65], v[4:5]
	v_mov_b64_e32 v[66:67], v[4:5]
	v_mov_b64_e32 v[68:69], v[4:5]
	v_mov_b64_e32 v[70:71], v[4:5]
	v_mov_b64_e32 v[72:73], v[4:5]
	v_mov_b64_e32 v[74:75], v[4:5]
	v_mov_b64_e32 v[76:77], v[4:5]
	v_mov_b64_e32 v[78:79], v[4:5]
	v_mov_b64_e32 v[80:81], v[4:5]
	v_mov_b64_e32 v[82:83], v[4:5]
	v_mov_b64_e32 v[84:85], v[4:5]
	v_mov_b64_e32 v[86:87], v[4:5]
	v_mov_b64_e32 v[88:89], v[4:5]
	v_mov_b64_e32 v[90:91], v[4:5]
	v_mov_b64_e32 v[92:93], v[4:5]
	v_mov_b64_e32 v[94:95], v[4:5]
	v_mov_b64_e32 v[96:97], v[4:5]
	v_mov_b64_e32 v[98:99], v[4:5]
	v_mov_b64_e32 v[100:101], v[4:5]
	v_mov_b64_e32 v[102:103], v[4:5]
	v_mov_b64_e32 v[104:105], v[4:5]
	v_mov_b64_e32 v[106:107], v[4:5]
	v_mov_b64_e32 v[108:109], v[4:5]
	v_mov_b64_e32 v[110:111], v[4:5]
	v_mov_b64_e32 v[112:113], v[4:5]
	v_mov_b64_e32 v[114:115], v[4:5]
	v_mov_b64_e32 v[116:117], v[4:5]
	v_mov_b64_e32 v[118:119], v[4:5]
	v_mov_b64_e32 v[120:121], v[4:5]
	v_mov_b64_e32 v[122:123], v[4:5]
	v_mov_b64_e32 v[140:141], v[4:5]
	v_mov_b64_e32 v[142:143], v[4:5]
	v_mov_b64_e32 v[144:145], v[4:5]
	v_mov_b64_e32 v[146:147], v[4:5]

;     __host__ __device__ bool next(int i, Unit& u) const { const int L = i * G + c; if (L >= nunits) return false; u.ks = L % KS; const int t = L / KS; u.pn = t % nN; u.pm = t / nN; return true; }
; template <class Epi, class Sched, bool ALIGN_EPI = false, bool SP2 = false>
; __device__ __forceinline__ void gemm_phase(PG8_LAS unsigned char* lds, const Gemm g, const Sched& S, const Epi& E) {
;     ...
;         const bool has_next = S.next(ui + 1, nxt);
;         const char* nA = has_next ? (const char*)g.A + (size_t)nxt.pm * tstep + (size_t)nxt.ks * K * 2 : cA; const char* nB = has_next ? (const char*)g.Bt + (size_t)nxt.pn * tstep + (size_t)nxt.ks * K * 2 : cB;
;     ...
; #pragma unroll
;         for (int a = 0; a < 2; ++a)
; #pragma unroll
;             for (int b = 0; b < 2; ++b)
; #pragma unroll
;                 for (int m = 0; m < 4; ++m)
; #pragma unroll
;                     for (int n = 0; n < 2; ++n) acc[a][b][m][n] = (f32x4){0.f, 0.f, 0.f, 0.f};
.LBB0_336:
	s_ashr_i32 s85, s84, 31
	s_lshl_b64 s[70:71], s[84:85], 19
	s_add_u32 s86, s75, s70
	s_addc_u32 s87, s76, s71
	s_and_b64 s[70:71], s[4:5], exec
	s_cselect_b32 s69, s87, s55
	s_cselect_b32 s85, s86, s54
	s_ashr_i32 s37, s36, 31
	s_lshl_b64 s[70:71], s[36:37], 19
	s_add_u32 s88, s83, s70
	s_addc_u32 s89, s8, s71
	s_and_b64 s[70:71], s[4:5], exec
	s_cselect_b32 s37, s89, s43
	s_cselect_b32 vcc_lo, s88, s42
	s_add_u32 vcc_hi, s42, 0x100
	s_addc_u32 s70, s43, 0
	s_add_u32 s92, s54, 0x40080
	v_mov_b32_e32 v4, 0
	s_addc_u32 s93, s55, 0
	s_mov_b32 s71, -2
	v_mov_b32_e32 v5, v4
	v_mov_b64_e32 v[6:7], v[4:5]
	v_mov_b64_e32 v[8:9], v[4:5]
	v_mov_b64_e32 v[10:11], v[4:5]
	v_mov_b64_e32 v[12:13], v[4:5]
	v_mov_b64_e32 v[14:15], v[4:5]
	v_mov_b64_e32 v[16:17], v[4:5]
	v_mov_b64_e32 v[18:19], v[4:5]
	v_mov_b64_e32 v[20:21], v[4:5]
	v_mov_b64_e32 v[22:23], v[4:5]
	v_mov_b64_e32 v[24:25], v[4:5]
	v_mov_b64_e32 v[26:27], v[4:5]
	v_mov_b64_e32 v[28:29], v[4:5]
	v_mov_b64_e32 v[30:31], v[4:5]
	v_mov_b64_e32 v[32:33], v[4:5]
	v_mov_b64_e32 v[34:35], v[4:5]
	v_mov_b64_e32 v[36:37], v[4:5]
	v_mov_b64_e32 v[38:39], v[4:5]
	v_mov_b64_e32 v[40:41], v[4:5]
	v_mov_b64_e32 v[42:43], v[4:5]
	v_mov_b64_e32 v[44:45], v[4:5]
	v_mov_b64_e32 v[46:47], v[4:5]
	v_mov_b64_e32 v[48:49], v[4:5]
	v_mov_b64_e32 v[50:51], v[4:5]
	v_mov_b64_e32 v[52:53], v[4:5]
	v_mov_b64_e32 v[54:55], v[4:5]
	v_mov_b64_e32 v[56:57], v[4:5]
	v_mov_b64_e32 v[58:59], v[4:5]
	v_mov_b64_e32 v[60:61], v[4:5]
	v_mov_b64_e32 v[62:63], v[4:5]
	v_mov_b64_e32 v[64:65], v[4:5]
	v_mov_b64_e32 v[66:67], v[4:5]
	v_mov_b64_e32 v[68:69], v[4:5]
	v_mov_b64_e32 v[70:71], v[4:5]
	v_mov_b64_e32 v[72:73], v[4:5]
	v_mov_b64_e32 v[74:75], v[4:5]
	v_mov_b64_e32 v[76:77], v[4:5]
	v_mov_b64_e32 v[78:79], v[4:5]
	v_mov_b64_e32 v[80:81], v[4:5]
	v_mov_b64_e32 v[82:83], v[4:5]
	v_mov_b64_e32 v[84:85], v[4:5]
	v_mov_b64_e32 v[86:87], v[4:5]
	v_mov_b64_e32 v[88:89], v[4:5]
	v_mov_b64_e32 v[90:91], v[4:5]
	v_mov_b64_e32 v[92:93], v[4:5]
	v_mov_b64_e32 v[94:95], v[4:5]
	v_mov_b64_e32 v[96:97], v[4:5]
	v_mov_b64_e32 v[98:99], v[4:5]
	v_mov_b64_e32 v[100:101], v[4:5]
	v_mov_b64_e32 v[102:103], v[4:5]
	v_mov_b64_e32 v[104:105], v[4:5]
	v_mov_b64_e32 v[106:107], v[4:5]
	v_mov_b64_e32 v[108:109], v[4:5]
	v_mov_b64_e32 v[110:111], v[4:5]
	v_mov_b64_e32 v[112:113], v[4:5]
	v_mov_b64_e32 v[114:115], v[4:5]
	v_mov_b64_e32 v[116:117], v[4:5]
	v_mov_b64_e32 v[118:119], v[4:5]
	v_mov_b64_e32 v[120:121], v[4:5]
	v_mov_b64_e32 v[122:123], v[4:5]
	v_mov_b64_e32 v[124:125], v[4:5]
	v_mov_b64_e32 v[126:127], v[4:5]
	v_mov_b64_e32 v[128:129], v[4:5]
	v_mov_b64_e32 v[130:131], v[4:5]

;     __host__ __device__ bool next(int i, Unit& u) const { const int L = i * G + c; if (L >= nunits) return false; u.ks = L % KS; const int t = L / KS; u.pn = t % nN; u.pm = t / nN; return true; }
; template <class Epi, class Sched, bool ALIGN_EPI = false, bool SP2 = false>
; __device__ __forceinline__ void gemm_phase(PG8_LAS unsigned char* lds, const Gemm g, const Sched& S, const Epi& E) {
;     ...
;         const bool has_next = S.next(ui + 1, nxt);
;         const char* nA = has_next ? (const char*)g.A + (size_t)nxt.pm * tstep + (size_t)nxt.ks * K * 2 : cA; const char* nB = has_next ? (const char*)g.Bt + (size_t)nxt.pn * tstep + (size_t)nxt.ks * K * 2 : cB;
;     ...
; #pragma unroll
;         for (int a = 0; a < 2; ++a)
; #pragma unroll
;             for (int b = 0; b < 2; ++b)
; #pragma unroll
;                 for (int m = 0; m < 4; ++m)
; #pragma unroll
;                     for (int n = 0; n < 2; ++n) acc[a][b][m][n] = (f32x4){0.f, 0.f, 0.f, 0.f};
.LBB0_427:
	s_ashr_i32 s85, s84, 31
	s_lshl_b64 s[68:69], s[84:85], 19
	s_add_u32 s86, s18, s68
	s_addc_u32 s87, s19, s69
	s_and_b64 s[68:69], s[4:5], exec
	s_cselect_b32 s67, s87, s55
	s_cselect_b32 s68, s86, s54
	s_ashr_i32 s37, s36, 31
	s_lshl_b64 s[70:71], s[36:37], 19
	s_add_u32 s88, s11, s70
	s_addc_u32 s89, s13, s71
	s_and_b64 s[70:71], s[4:5], exec
	s_cselect_b32 s37, s89, s43
	s_cselect_b32 s69, s88, s42
	s_add_u32 s82, s42, 0x100
	s_addc_u32 s83, s43, 0
	s_add_u32 s92, s54, 0x40080
	v_mov_b32_e32 v4, 0
	s_addc_u32 s93, s55, 0
	s_mov_b32 s70, -2
	v_mov_b32_e32 v5, v4
	v_mov_b64_e32 v[6:7], v[4:5]
	v_mov_b64_e32 v[8:9], v[4:5]
	v_mov_b64_e32 v[10:11], v[4:5]
	v_mov_b64_e32 v[12:13], v[4:5]
	v_mov_b64_e32 v[14:15], v[4:5]
	v_mov_b64_e32 v[16:17], v[4:5]
	v_mov_b64_e32 v[18:19], v[4:5]
	v_mov_b64_e32 v[20:21], v[4:5]
	v_mov_b64_e32 v[22:23], v[4:5]
	v_mov_b64_e32 v[24:25], v[4:5]
	v_mov_b64_e32 v[26:27], v[4:5]
	v_mov_b64_e32 v[28:29], v[4:5]
	v_mov_b64_e32 v[30:31], v[4:5]
	v_mov_b64_e32 v[32:33], v[4:5]
	v_mov_b64_e32 v[34:35], v[4:5]
	v_mov_b64_e32 v[36:37], v[4:5]
	v_mov_b64_e32 v[38:39], v[4:5]
	v_mov_b64_e32 v[40:41], v[4:5]
	v_mov_b64_e32 v[42:43], v[4:5]
	v_mov_b64_e32 v[44:45], v[4:5]
	v_mov_b64_e32 v[46:47], v[4:5]
	v_mov_b64_e32 v[48:49], v[4:5]
	v_mov_b64_e32 v[50:51], v[4:5]
	v_mov_b64_e32 v[52:53], v[4:5]
	v_mov_b64_e32 v[54:55], v[4:5]
	v_mov_b64_e32 v[56:57], v[4:5]
	v_mov_b64_e32 v[58:59], v[4:5]
	v_mov_b64_e32 v[60:61], v[4:5]
	v_mov_b64_e32 v[62:63], v[4:5]
	v_mov_b64_e32 v[64:65], v[4:5]
	v_mov_b64_e32 v[66:67], v[4:5]
	v_mov_b64_e32 v[68:69], v[4:5]
	v_mov_b64_e32 v[70:71], v[4:5]
	v_mov_b64_e32 v[72:73], v[4:5]
	v_mov_b64_e32 v[74:75], v[4:5]
	v_mov_b64_e32 v[76:77], v[4:5]
	v_mov_b64_e32 v[78:79], v[4:5]
	v_mov_b64_e32 v[80:81], v[4:5]
	v_mov_b64_e32 v[82:83], v[4:5]
	v_mov_b64_e32 v[84:85], v[4:5]
	v_mov_b64_e32 v[86:87], v[4:5]
	v_mov_b64_e32 v[88:89], v[4:5]
	v_mov_b64_e32 v[90:91], v[4:5]
	v_mov_b64_e32 v[92:93], v[4:5]
	v_mov_b64_e32 v[94:95], v[4:5]
	v_mov_b64_e32 v[96:97], v[4:5]
	v_mov_b64_e32 v[98:99], v[4:5]
	v_mov_b64_e32 v[100:101], v[4:5]
	v_mov_b64_e32 v[102:103], v[4:5]
	v_mov_b64_e32 v[104:105], v[4:5]
	v_mov_b64_e32 v[106:107], v[4:5]
	v_mov_b64_e32 v[108:109], v[4:5]
	v_mov_b64_e32 v[110:111], v[4:5]
	v_mov_b64_e32 v[112:113], v[4:5]
	v_mov_b64_e32 v[114:115], v[4:5]
	v_mov_b64_e32 v[116:117], v[4:5]
	v_mov_b64_e32 v[118:119], v[4:5]
	v_mov_b64_e32 v[120:121], v[4:5]
	v_mov_b64_e32 v[122:123], v[4:5]
	v_mov_b64_e32 v[140:141], v[4:5]
	v_mov_b64_e32 v[142:143], v[4:5]
	v_mov_b64_e32 v[144:145], v[4:5]
	v_mov_b64_e32 v[146:147], v[4:5]

;     __host__ __device__ bool next(int i, Unit& u) const { const int L = i * G + c; if (L >= nunits) return false; u.ks = L % KS; const int t = L / KS; u.pn = t % nN; u.pm = t / nN; return true; }
; template <class Epi, class Sched, bool ALIGN_EPI = false, bool SP2 = false>
; __device__ __forceinline__ void gemm_phase(PG8_LAS unsigned char* lds, const Gemm g, const Sched& S, const Epi& E) {
;     ...
;         const bool has_next = S.next(ui + 1, nxt);
;         const char* nA = has_next ? (const char*)g.A + (size_t)nxt.pm * tstep + (size_t)nxt.ks * K * 2 : cA; const char* nB = has_next ? (const char*)g.Bt + (size_t)nxt.pn * tstep + (size_t)nxt.ks * K * 2 : cB;
;     ...
; #pragma unroll
;         for (int a = 0; a < 2; ++a)
; #pragma unroll
;             for (int b = 0; b < 2; ++b)
; #pragma unroll
;                 for (int m = 0; m < 4; ++m)
; #pragma unroll
;                     for (int n = 0; n < 2; ++n) acc[a][b][m][n] = (f32x4){0.f, 0.f, 0.f, 0.f};
.LBB0_552:
	s_ashr_i32 s27, s26, 31
	s_lshl_b64 s[28:29], s[26:27], 19
	s_add_u32 s28, s75, s28
	s_addc_u32 s29, s76, s29
	s_and_b64 s[30:31], s[4:5], exec
	s_cselect_b32 s27, s29, s43
	s_cselect_b32 s65, s28, s42
	s_ashr_i32 s25, s24, 31
	s_lshl_b64 s[30:31], s[24:25], 19
	s_add_u32 s30, s1, s30
	s_addc_u32 s31, s3, s31
	s_and_b64 s[54:55], s[4:5], exec
	s_cselect_b32 s25, s31, s37
	s_cselect_b32 s66, s30, s36
	s_add_u32 s67, s36, 0x100
	s_addc_u32 s68, s37, 0
	s_add_u32 s36, s42, 0x40080
	v_mov_b32_e32 v4, 0
	s_addc_u32 s37, s43, 0
	s_mov_b32 s69, -2
	v_mov_b32_e32 v5, v4
	v_mov_b64_e32 v[6:7], v[4:5]
	v_mov_b64_e32 v[8:9], v[4:5]
	v_mov_b64_e32 v[10:11], v[4:5]
	v_mov_b64_e32 v[12:13], v[4:5]
	v_mov_b64_e32 v[14:15], v[4:5]
	v_mov_b64_e32 v[16:17], v[4:5]
	v_mov_b64_e32 v[18:19], v[4:5]
	v_mov_b64_e32 v[20:21], v[4:5]
	v_mov_b64_e32 v[22:23], v[4:5]
	v_mov_b64_e32 v[24:25], v[4:5]
	v_mov_b64_e32 v[26:27], v[4:5]
	v_mov_b64_e32 v[28:29], v[4:5]
	v_mov_b64_e32 v[30:31], v[4:5]
	v_mov_b64_e32 v[32:33], v[4:5]
	v_mov_b64_e32 v[34:35], v[4:5]
	v_mov_b64_e32 v[36:37], v[4:5]
	v_mov_b64_e32 v[38:39], v[4:5]
	v_mov_b64_e32 v[40:41], v[4:5]
	v_mov_b64_e32 v[42:43], v[4:5]
	v_mov_b64_e32 v[44:45], v[4:5]
	v_mov_b64_e32 v[46:47], v[4:5]
	v_mov_b64_e32 v[48:49], v[4:5]
	v_mov_b64_e32 v[50:51], v[4:5]
	v_mov_b64_e32 v[52:53], v[4:5]
	v_mov_b64_e32 v[54:55], v[4:5]
	v_mov_b64_e32 v[56:57], v[4:5]
	v_mov_b64_e32 v[58:59], v[4:5]
	v_mov_b64_e32 v[60:61], v[4:5]
	v_mov_b64_e32 v[62:63], v[4:5]
	v_mov_b64_e32 v[64:65], v[4:5]
	v_mov_b64_e32 v[66:67], v[4:5]
	v_mov_b64_e32 v[68:69], v[4:5]
	v_mov_b64_e32 v[70:71], v[4:5]
	v_mov_b64_e32 v[72:73], v[4:5]
	v_mov_b64_e32 v[74:75], v[4:5]
	v_mov_b64_e32 v[76:77], v[4:5]
	v_mov_b64_e32 v[78:79], v[4:5]
	v_mov_b64_e32 v[80:81], v[4:5]
	v_mov_b64_e32 v[82:83], v[4:5]
	v_mov_b64_e32 v[84:85], v[4:5]
	v_mov_b64_e32 v[86:87], v[4:5]
	v_mov_b64_e32 v[88:89], v[4:5]
	v_mov_b64_e32 v[90:91], v[4:5]
	v_mov_b64_e32 v[92:93], v[4:5]
	v_mov_b64_e32 v[94:95], v[4:5]
	v_mov_b64_e32 v[96:97], v[4:5]
	v_mov_b64_e32 v[98:99], v[4:5]
	v_mov_b64_e32 v[100:101], v[4:5]
	v_mov_b64_e32 v[102:103], v[4:5]
	v_mov_b64_e32 v[104:105], v[4:5]
	v_mov_b64_e32 v[106:107], v[4:5]
	v_mov_b64_e32 v[108:109], v[4:5]
	v_mov_b64_e32 v[110:111], v[4:5]
	v_mov_b64_e32 v[112:113], v[4:5]
	v_mov_b64_e32 v[114:115], v[4:5]
	v_mov_b64_e32 v[116:117], v[4:5]
	v_mov_b64_e32 v[118:119], v[4:5]
	v_mov_b64_e32 v[120:121], v[4:5]
	v_mov_b64_e32 v[122:123], v[4:5]
	v_mov_b64_e32 v[124:125], v[4:5]
	v_mov_b64_e32 v[126:127], v[4:5]
	v_mov_b64_e32 v[128:129], v[4:5]
	v_mov_b64_e32 v[130:131], v[4:5]
